# P3 pass-0 merge epilogue: 32 gate loads issued up front with one counted wait (was load + vmcnt(0) per accumulator quad), on top of the P1 rope rewrite
# baseline (speedup 1.0000x reference)
; DI unsigned pk2(float a, float b) { f32x2 v = {a, b}; return __builtin_bit_cast(unsigned, __builtin_convertvector(v, bfv2)); }
; DI float bflo(unsigned u) { return __uint_as_float(u << 16); }
; DI float bfhi(unsigned u) { return __uint_as_float(u & 0xffff0000u); }
;     DI void operator()(const pg8::f32x4 (&acc)[2][2][4][2], const pg8::Unit& u, int wr, int wc, int fr, int fq) const {
;     ...
;         for (int ai = 0; ai < 2; ++ai)
; #pragma unroll
;             for (int m = 0; m < 4; ++m) {
;                 const size_t tok = (size_t)u.pm * 256 + ai * 128 + wr * 64 + m * 16 + fr;
; #pragma unroll
;                 for (int bj = 0; bj < 2; ++bj)
; #pragma unroll
;                     for (int n = 0; n < 2; ++n) {
;                         const size_t off = tok * 1024 + u.pn * 256 + bj * 128 + wc * 32 + n * 16 + 4 * fq;
;                         const unsigned ug = *(const unsigned*)(sg + off);
;                         const float q = (PASS == 0 ? tab[(ai * 128 + wr * 64 + m * 16 + fr) * 4 + 3] : 1.0f) * (1.0f / 255.0f);
;                         float m0 = (float)(ug & 255u) * q * acc[ai][bj][m][n][0], m1 = (float)((ug >> 8) & 255u) * q * acc[ai][bj][m][n][1];
;                         float m2 = (float)((ug >> 16) & 255u) * q * acc[ai][bj][m][n][2], m3 = (float)(ug >> 24) * q * acc[ai][bj][m][n][3];
;                         if (PASS == 1) { const u32x2 t = *(const u32x2*)(merged + off); m0 += bflo(t.x); m1 += bfhi(t.x); m2 += bflo(t.y); m3 += bfhi(t.y); }
;                         u32x2 o; o.x = pk2(m0, m1); o.y = pk2(m2, m3);
;                         *(u32x2*)(merged + off) = o;
.LBB0_1921:
	s_lshl_b64 s[28:29], s[12:13], 18
	s_lshl_b32 s26, s2, 8
	v_lshl_add_u64 v[2:3], s[28:29], 0, v[138:139]
	s_ashr_i32 s27, s26, 31
	v_lshl_add_u64 v[220:221], s[28:29], 0, v[138:139]
	v_lshl_add_u64 v[222:223], v[220:221], 0, s[26:27]
	v_or_b32_e32 v222, v222, v136
	v_lshl_add_u64 v[174:175], s[22:23], 0, v[222:223]
	global_load_dword v188, v[174:175], off
	v_or_b32_e32 v222, 16, v222
	v_lshl_add_u64 v[176:177], s[22:23], 0, v[222:223]
	global_load_dword v189, v[176:177], off
	v_or_b32_e32 v226, s26, v146
	v_mov_b32_e32 v227, s27
	v_lshl_add_u64 v[224:225], v[220:221], 0, v[226:227]
	v_lshl_add_u64 v[174:175], s[22:23], 0, v[224:225]
	global_load_dword v190, v[174:175], off
	v_or_b32_e32 v224, 16, v224
	v_lshl_add_u64 v[176:177], s[22:23], 0, v[224:225]
	global_load_dword v191, v[176:177], off
	v_lshl_add_u64 v[220:221], s[28:29], 0, v[140:141]
	v_lshl_add_u64 v[222:223], v[220:221], 0, s[26:27]
	v_or_b32_e32 v222, v222, v136
	v_lshl_add_u64 v[174:175], s[22:23], 0, v[222:223]
	global_load_dword v192, v[174:175], off
	v_or_b32_e32 v222, 16, v222
	v_lshl_add_u64 v[176:177], s[22:23], 0, v[222:223]
	global_load_dword v193, v[176:177], off
	v_or_b32_e32 v220, v220, v146
	v_lshl_add_u64 v[224:225], v[220:221], 0, s[26:27]
	v_lshl_add_u64 v[174:175], s[22:23], 0, v[224:225]
	global_load_dword v194, v[174:175], off
	v_or_b32_e32 v224, 16, v224
	v_lshl_add_u64 v[176:177], s[22:23], 0, v[224:225]
	global_load_dword v195, v[176:177], off
	v_lshl_add_u64 v[220:221], s[28:29], 0, v[142:143]
	v_lshl_add_u64 v[222:223], v[220:221], 0, s[26:27]
	v_or_b32_e32 v222, v222, v136
	v_lshl_add_u64 v[174:175], s[22:23], 0, v[222:223]
	global_load_dword v196, v[174:175], off
	v_or_b32_e32 v222, 16, v222
	v_lshl_add_u64 v[176:177], s[22:23], 0, v[222:223]
	global_load_dword v197, v[176:177], off
	v_or_b32_e32 v220, v220, v146
	v_lshl_add_u64 v[224:225], v[220:221], 0, s[26:27]
	v_lshl_add_u64 v[174:175], s[22:23], 0, v[224:225]
	global_load_dword v198, v[174:175], off
	v_or_b32_e32 v224, 16, v224
	v_lshl_add_u64 v[176:177], s[22:23], 0, v[224:225]
	global_load_dword v199, v[176:177], off
	v_lshl_add_u64 v[220:221], s[28:29], 0, v[144:145]
	v_lshl_add_u64 v[222:223], v[220:221], 0, s[26:27]
	v_or_b32_e32 v222, v222, v136
	v_lshl_add_u64 v[174:175], s[22:23], 0, v[222:223]
	global_load_dword v200, v[174:175], off
	v_or_b32_e32 v222, 16, v222
	v_lshl_add_u64 v[176:177], s[22:23], 0, v[222:223]
	global_load_dword v201, v[176:177], off
	v_or_b32_e32 v220, v220, v146
	v_lshl_add_u64 v[224:225], v[220:221], 0, s[26:27]
	v_lshl_add_u64 v[174:175], s[22:23], 0, v[224:225]
	global_load_dword v202, v[174:175], off
	v_or_b32_e32 v224, 16, v224
	v_lshl_add_u64 v[176:177], s[22:23], 0, v[224:225]
	global_load_dword v203, v[176:177], off
	v_lshl_add_u64 v[220:221], s[28:29], 0, v[148:149]
	v_lshl_add_u64 v[222:223], v[220:221], 0, s[26:27]
	v_or_b32_e32 v222, v222, v136
	v_lshl_add_u64 v[174:175], s[22:23], 0, v[222:223]
	global_load_dword v204, v[174:175], off
	v_or_b32_e32 v222, 16, v222
	v_lshl_add_u64 v[176:177], s[22:23], 0, v[222:223]
	global_load_dword v205, v[176:177], off
	v_or_b32_e32 v220, v220, v146
	v_lshl_add_u64 v[224:225], v[220:221], 0, s[26:27]
	v_lshl_add_u64 v[174:175], s[22:23], 0, v[224:225]
	global_load_dword v206, v[174:175], off
	v_or_b32_e32 v224, 16, v224
	v_lshl_add_u64 v[176:177], s[22:23], 0, v[224:225]
	global_load_dword v207, v[176:177], off
	v_lshl_add_u64 v[220:221], s[28:29], 0, v[150:151]
	v_lshl_add_u64 v[222:223], v[220:221], 0, s[26:27]
	v_or_b32_e32 v222, v222, v136
	v_lshl_add_u64 v[174:175], s[22:23], 0, v[222:223]
	global_load_dword v208, v[174:175], off
	v_or_b32_e32 v222, 16, v222
	v_lshl_add_u64 v[176:177], s[22:23], 0, v[222:223]
	global_load_dword v209, v[176:177], off
	v_or_b32_e32 v220, v220, v146
	v_lshl_add_u64 v[224:225], v[220:221], 0, s[26:27]
	v_lshl_add_u64 v[174:175], s[22:23], 0, v[224:225]
	global_load_dword v210, v[174:175], off
	v_or_b32_e32 v224, 16, v224
	v_lshl_add_u64 v[176:177], s[22:23], 0, v[224:225]
	global_load_dword v211, v[176:177], off
	v_lshl_add_u64 v[220:221], s[28:29], 0, v[152:153]
	v_lshl_add_u64 v[222:223], v[220:221], 0, s[26:27]
	v_or_b32_e32 v222, v222, v136
	v_lshl_add_u64 v[174:175], s[22:23], 0, v[222:223]
	global_load_dword v212, v[174:175], off
	v_or_b32_e32 v222, 16, v222
	v_lshl_add_u64 v[176:177], s[22:23], 0, v[222:223]
	global_load_dword v213, v[176:177], off
	v_or_b32_e32 v220, v220, v146
	v_lshl_add_u64 v[224:225], v[220:221], 0, s[26:27]
	v_lshl_add_u64 v[174:175], s[22:23], 0, v[224:225]
	global_load_dword v214, v[174:175], off
	v_or_b32_e32 v224, 16, v224
	v_lshl_add_u64 v[176:177], s[22:23], 0, v[224:225]
	global_load_dword v215, v[176:177], off
	v_lshl_add_u64 v[220:221], s[28:29], 0, v[154:155]
	v_lshl_add_u64 v[222:223], v[220:221], 0, s[26:27]
	v_or_b32_e32 v222, v222, v136
	v_lshl_add_u64 v[174:175], s[22:23], 0, v[222:223]
	global_load_dword v216, v[174:175], off
	v_or_b32_e32 v222, 16, v222
	v_lshl_add_u64 v[176:177], s[22:23], 0, v[222:223]
	global_load_dword v217, v[176:177], off
	v_or_b32_e32 v220, v220, v146
	v_lshl_add_u64 v[224:225], v[220:221], 0, s[26:27]
	v_lshl_add_u64 v[174:175], s[22:23], 0, v[224:225]
	global_load_dword v218, v[174:175], off
	v_or_b32_e32 v224, 16, v224
	v_lshl_add_u64 v[176:177], s[22:23], 0, v[224:225]
	global_load_dword v219, v[176:177], off
	v_lshl_add_u64 v[162:163], v[2:3], 0, s[26:27]
	v_or_b32_e32 v162, v162, v136
	ds_read2_b32 v[164:165], v161 offset0:3 offset1:67
	v_lshl_add_u64 v[166:167], v[162:163], 1, s[44:45]
	v_or_b32_e32 v162, 16, v162
	s_andn2_b64 vcc, exec, s[24:25]
	s_waitcnt lgkmcnt(0)
; DI unsigned pk2(float a, float b) { f32x2 v = {a, b}; return __builtin_bit_cast(unsigned, __builtin_convertvector(v, bfv2)); }
; DI float bflo(unsigned u) { return __uint_as_float(u << 16); }
; DI float bfhi(unsigned u) { return __uint_as_float(u & 0xffff0000u); }
;     DI void operator()(const pg8::f32x4 (&acc)[2][2][4][2], const pg8::Unit& u, int wr, int wc, int fr, int fq) const {
;     ...
;                 const size_t tok = (size_t)u.pm * 256 + ai * 128 + wr * 64 + m * 16 + fr;
; #pragma unroll
;                 for (int bj = 0; bj < 2; ++bj)
; #pragma unroll
;                     for (int n = 0; n < 2; ++n) {
;                         const size_t off = tok * 1024 + u.pn * 256 + bj * 128 + wc * 32 + n * 16 + 4 * fq;
;                         const unsigned ug = *(const unsigned*)(sg + off);
;                         const float q = (PASS == 0 ? tab[(ai * 128 + wr * 64 + m * 16 + fr) * 4 + 3] : 1.0f) * (1.0f / 255.0f);
;                         float m0 = (float)(ug & 255u) * q * acc[ai][bj][m][n][0], m1 = (float)((ug >> 8) & 255u) * q * acc[ai][bj][m][n][1];
;                         float m2 = (float)((ug >> 16) & 255u) * q * acc[ai][bj][m][n][2], m3 = (float)(ug >> 24) * q * acc[ai][bj][m][n][3];
;                         if (PASS == 1) { const u32x2 t = *(const u32x2*)(merged + off); m0 += bflo(t.x); m1 += bfhi(t.x); m2 += bflo(t.y); m3 += bfhi(t.y); }
;                         u32x2 o; o.x = pk2(m0, m1); o.y = pk2(m2, m3);
;                         *(u32x2*)(merged + off) = o;
	v_mul_f32_e32 v164, 0x3b808081, v164
	s_mov_b64 s[24:25], -1
	s_waitcnt vmcnt(31)
	v_cvt_f32_ubyte1_e32 v171, v188
	v_cvt_f32_ubyte0_e32 v170, v188
	v_cvt_f32_ubyte3_e32 v173, v188
	v_cvt_f32_ubyte2_e32 v172, v188
	v_pk_mul_f32 v[170:171], v[164:165], v[170:171] op_sel_hi:[0,1]
	v_pk_mul_f32 v[172:173], v[164:165], v[172:173] op_sel_hi:[0,1]
	v_pk_mul_f32 v[128:129], v[128:129], v[170:171]
	v_pk_mul_f32 v[130:131], v[130:131], v[172:173]
	v_cvt_pk_bf16_f32 v128, v128, v129
	v_cvt_pk_bf16_f32 v129, v130, v131
	global_store_dwordx2 v[166:167], v[128:129], off
	v_lshl_add_u64 v[130:131], v[162:163], 1, s[44:45]
	v_or_b32_e32 v128, s26, v146
	v_mov_b32_e32 v129, s27
	v_lshl_add_u64 v[2:3], v[2:3], 0, v[128:129]
	s_waitcnt vmcnt(31)
	v_cvt_f32_ubyte1_e32 v163, v189
	v_cvt_f32_ubyte0_e32 v162, v189
	v_cvt_f32_ubyte3_e32 v167, v189
	v_cvt_f32_ubyte2_e32 v166, v189
	v_pk_mul_f32 v[162:163], v[164:165], v[162:163] op_sel_hi:[0,1]
	v_pk_mul_f32 v[166:167], v[164:165], v[166:167] op_sel_hi:[0,1]
	v_pk_mul_f32 v[124:125], v[124:125], v[162:163]
	v_pk_mul_f32 v[126:127], v[126:127], v[166:167]
	v_cvt_pk_bf16_f32 v124, v124, v125
	v_cvt_pk_bf16_f32 v125, v126, v127
	global_store_dwordx2 v[130:131], v[124:125], off
	v_lshl_add_u64 v[124:125], v[2:3], 1, s[44:45]
	v_or_b32_e32 v2, 16, v2
	v_lshl_add_u64 v[2:3], v[2:3], 1, s[44:45]
	s_waitcnt vmcnt(31)
	v_cvt_f32_ubyte1_e32 v129, v190
	v_cvt_f32_ubyte0_e32 v128, v190
	v_cvt_f32_ubyte3_e32 v131, v190
	v_cvt_f32_ubyte2_e32 v130, v190
	v_pk_mul_f32 v[128:129], v[164:165], v[128:129] op_sel_hi:[0,1]
	v_pk_mul_f32 v[130:131], v[164:165], v[130:131] op_sel_hi:[0,1]
	v_pk_mul_f32 v[120:121], v[120:121], v[128:129]
	v_pk_mul_f32 v[122:123], v[122:123], v[130:131]
	v_cvt_pk_bf16_f32 v120, v120, v121
	v_cvt_pk_bf16_f32 v121, v122, v123
	global_store_dwordx2 v[124:125], v[120:121], off
	v_lshl_add_u64 v[120:121], s[28:29], 0, v[140:141]
	v_lshl_add_u64 v[122:123], v[120:121], 0, s[26:27]
	v_or_b32_e32 v122, v122, v136
	v_or_b32_e32 v120, v120, v146
	s_waitcnt vmcnt(31)
	v_cvt_f32_ubyte1_e32 v127, v191
	v_cvt_f32_ubyte0_e32 v126, v191
	v_cvt_f32_ubyte3_e32 v129, v191
	v_cvt_f32_ubyte2_e32 v128, v191
	v_pk_mul_f32 v[126:127], v[164:165], v[126:127] op_sel_hi:[0,1]
	v_pk_mul_f32 v[128:129], v[164:165], v[128:129] op_sel_hi:[0,1]
	v_pk_mul_f32 v[116:117], v[116:117], v[126:127]
	v_pk_mul_f32 v[118:119], v[118:119], v[128:129]
	v_cvt_pk_bf16_f32 v116, v116, v117
	v_cvt_pk_bf16_f32 v117, v118, v119
	global_store_dwordx2 v[2:3], v[116:117], off
	v_mul_f32_e32 v116, 0x3b808081, v165
	v_lshl_add_u64 v[2:3], v[122:123], 1, s[44:45]
	v_or_b32_e32 v122, 16, v122
	s_waitcnt vmcnt(31)
	v_cvt_f32_ubyte1_e32 v125, v192
	v_cvt_f32_ubyte0_e32 v124, v192
	v_cvt_f32_ubyte3_e32 v127, v192
	v_cvt_f32_ubyte2_e32 v126, v192
	v_pk_mul_f32 v[124:125], v[116:117], v[124:125] op_sel_hi:[0,1]
	v_pk_mul_f32 v[126:127], v[116:117], v[126:127] op_sel_hi:[0,1]
	v_pk_mul_f32 v[112:113], v[112:113], v[124:125]
	v_pk_mul_f32 v[114:115], v[114:115], v[126:127]
	v_cvt_pk_bf16_f32 v112, v112, v113
	v_cvt_pk_bf16_f32 v113, v114, v115
	global_store_dwordx2 v[2:3], v[112:113], off
	v_lshl_add_u64 v[2:3], v[120:121], 0, s[26:27]
	v_lshl_add_u64 v[114:115], v[122:123], 1, s[44:45]
	s_waitcnt vmcnt(31)
	v_cvt_f32_ubyte1_e32 v119, v193
	v_cvt_f32_ubyte0_e32 v118, v193
	v_cvt_f32_ubyte3_e32 v121, v193
	v_cvt_f32_ubyte2_e32 v120, v193
	v_pk_mul_f32 v[118:119], v[116:117], v[118:119] op_sel_hi:[0,1]
	v_pk_mul_f32 v[120:121], v[116:117], v[120:121] op_sel_hi:[0,1]
	v_pk_mul_f32 v[108:109], v[108:109], v[118:119]
	v_pk_mul_f32 v[110:111], v[110:111], v[120:121]
	v_cvt_pk_bf16_f32 v108, v108, v109
	v_cvt_pk_bf16_f32 v109, v110, v111
	global_store_dwordx2 v[114:115], v[108:109], off
	v_lshl_add_u64 v[108:109], v[2:3], 1, s[44:45]
	v_or_b32_e32 v2, 16, v2
	v_lshl_add_u64 v[2:3], v[2:3], 1, s[44:45]
	s_waitcnt vmcnt(31)
	v_cvt_f32_ubyte1_e32 v113, v194
	v_cvt_f32_ubyte0_e32 v112, v194
	v_cvt_f32_ubyte3_e32 v115, v194
	v_cvt_f32_ubyte2_e32 v114, v194
	v_pk_mul_f32 v[112:113], v[116:117], v[112:113] op_sel_hi:[0,1]
	v_pk_mul_f32 v[114:115], v[116:117], v[114:115] op_sel_hi:[0,1]
	v_pk_mul_f32 v[104:105], v[104:105], v[112:113]
	v_pk_mul_f32 v[106:107], v[106:107], v[114:115]
	v_cvt_pk_bf16_f32 v104, v104, v105
	v_cvt_pk_bf16_f32 v105, v106, v107
	global_store_dwordx2 v[108:109], v[104:105], off
	v_lshl_add_u64 v[104:105], s[28:29], 0, v[142:143]
	v_lshl_add_u64 v[106:107], v[104:105], 0, s[26:27]
	v_or_b32_e32 v106, v106, v136
	v_or_b32_e32 v104, v104, v146
	s_waitcnt vmcnt(31)
	v_cvt_f32_ubyte1_e32 v111, v195
	v_cvt_f32_ubyte0_e32 v110, v195
	v_cvt_f32_ubyte3_e32 v113, v195
	v_cvt_f32_ubyte2_e32 v112, v195
	v_pk_mul_f32 v[110:111], v[116:117], v[110:111] op_sel_hi:[0,1]
	v_pk_mul_f32 v[112:113], v[116:117], v[112:113] op_sel_hi:[0,1]
	v_pk_mul_f32 v[100:101], v[100:101], v[110:111]
	v_pk_mul_f32 v[102:103], v[102:103], v[112:113]
	v_cvt_pk_bf16_f32 v100, v100, v101
	v_cvt_pk_bf16_f32 v101, v102, v103
	global_store_dwordx2 v[2:3], v[100:101], off
	ds_read2_b32 v[2:3], v161 offset0:131 offset1:195
	v_lshl_add_u64 v[100:101], v[106:107], 1, s[44:45]
	v_or_b32_e32 v106, 16, v106
	s_waitcnt lgkmcnt(0)
	v_mul_f32_e32 v2, 0x3b808081, v2
	s_waitcnt vmcnt(31)
	v_cvt_f32_ubyte1_e32 v109, v196
	v_cvt_f32_ubyte0_e32 v108, v196
	v_cvt_f32_ubyte3_e32 v111, v196
	v_cvt_f32_ubyte2_e32 v110, v196
	v_pk_mul_f32 v[108:109], v[2:3], v[108:109] op_sel_hi:[0,1]
	v_pk_mul_f32 v[110:111], v[2:3], v[110:111] op_sel_hi:[0,1]
	v_pk_mul_f32 v[96:97], v[96:97], v[108:109]
	v_pk_mul_f32 v[98:99], v[98:99], v[110:111]
	v_cvt_pk_bf16_f32 v96, v96, v97
	v_cvt_pk_bf16_f32 v97, v98, v99
	global_store_dwordx2 v[100:101], v[96:97], off
	v_lshl_add_u64 v[96:97], v[104:105], 0, s[26:27]
	v_lshl_add_u64 v[100:101], v[106:107], 1, s[44:45]
	s_waitcnt vmcnt(31)
; DI unsigned pk2(float a, float b) { f32x2 v = {a, b}; return __builtin_bit_cast(unsigned, __builtin_convertvector(v, bfv2)); }
; DI float bflo(unsigned u) { return __uint_as_float(u << 16); }
; DI float bfhi(unsigned u) { return __uint_as_float(u & 0xffff0000u); }
;     DI void operator()(const pg8::f32x4 (&acc)[2][2][4][2], const pg8::Unit& u, int wr, int wc, int fr, int fq) const {
;     ...
;                 const size_t tok = (size_t)u.pm * 256 + ai * 128 + wr * 64 + m * 16 + fr;
; #pragma unroll
;                 for (int bj = 0; bj < 2; ++bj)
; #pragma unroll
;                     for (int n = 0; n < 2; ++n) {
;                         const size_t off = tok * 1024 + u.pn * 256 + bj * 128 + wc * 32 + n * 16 + 4 * fq;
;                         const unsigned ug = *(const unsigned*)(sg + off);
;                         const float q = (PASS == 0 ? tab[(ai * 128 + wr * 64 + m * 16 + fr) * 4 + 3] : 1.0f) * (1.0f / 255.0f);
;                         float m0 = (float)(ug & 255u) * q * acc[ai][bj][m][n][0], m1 = (float)((ug >> 8) & 255u) * q * acc[ai][bj][m][n][1];
;                         float m2 = (float)((ug >> 16) & 255u) * q * acc[ai][bj][m][n][2], m3 = (float)(ug >> 24) * q * acc[ai][bj][m][n][3];
;                         if (PASS == 1) { const u32x2 t = *(const u32x2*)(merged + off); m0 += bflo(t.x); m1 += bfhi(t.x); m2 += bflo(t.y); m3 += bfhi(t.y); }
;                         u32x2 o; o.x = pk2(m0, m1); o.y = pk2(m2, m3);
;                         *(u32x2*)(merged + off) = o;
	v_cvt_f32_ubyte1_e32 v103, v197
	v_cvt_f32_ubyte0_e32 v102, v197
	v_cvt_f32_ubyte3_e32 v105, v197
	v_cvt_f32_ubyte2_e32 v104, v197
	v_pk_mul_f32 v[102:103], v[2:3], v[102:103] op_sel_hi:[0,1]
	v_pk_mul_f32 v[104:105], v[2:3], v[104:105] op_sel_hi:[0,1]
	v_pk_mul_f32 v[92:93], v[92:93], v[102:103]
	v_pk_mul_f32 v[94:95], v[94:95], v[104:105]
	v_cvt_pk_bf16_f32 v92, v92, v93
	v_cvt_pk_bf16_f32 v93, v94, v95
	global_store_dwordx2 v[100:101], v[92:93], off
	v_lshl_add_u64 v[92:93], v[96:97], 1, s[44:45]
	v_or_b32_e32 v96, 16, v96
	s_waitcnt vmcnt(31)
	v_cvt_f32_ubyte1_e32 v99, v198
	v_cvt_f32_ubyte0_e32 v98, v198
	v_cvt_f32_ubyte3_e32 v101, v198
	v_cvt_f32_ubyte2_e32 v100, v198
	v_pk_mul_f32 v[98:99], v[2:3], v[98:99] op_sel_hi:[0,1]
	v_pk_mul_f32 v[100:101], v[2:3], v[100:101] op_sel_hi:[0,1]
	v_pk_mul_f32 v[88:89], v[88:89], v[98:99]
	v_pk_mul_f32 v[90:91], v[90:91], v[100:101]
	v_cvt_pk_bf16_f32 v88, v88, v89
	v_cvt_pk_bf16_f32 v89, v90, v91
	global_store_dwordx2 v[92:93], v[88:89], off
	v_lshl_add_u64 v[94:95], v[96:97], 1, s[44:45]
	v_lshl_add_u64 v[88:89], s[28:29], 0, v[144:145]
	v_lshl_add_u64 v[90:91], v[88:89], 0, s[26:27]
	v_or_b32_e32 v90, v90, v136
	v_or_b32_e32 v88, v88, v146
	s_waitcnt vmcnt(31)
	v_cvt_f32_ubyte1_e32 v97, v199
	v_cvt_f32_ubyte0_e32 v96, v199
	v_cvt_f32_ubyte3_e32 v99, v199
	v_cvt_f32_ubyte2_e32 v98, v199
	v_pk_mul_f32 v[96:97], v[2:3], v[96:97] op_sel_hi:[0,1]
	v_pk_mul_f32 v[98:99], v[2:3], v[98:99] op_sel_hi:[0,1]
	v_pk_mul_f32 v[84:85], v[84:85], v[96:97]
	v_pk_mul_f32 v[86:87], v[86:87], v[98:99]
	v_cvt_pk_bf16_f32 v84, v84, v85
	v_cvt_pk_bf16_f32 v85, v86, v87
	global_store_dwordx2 v[94:95], v[84:85], off
	v_mul_f32_e32 v2, 0x3b808081, v3
	v_lshl_add_u64 v[84:85], v[90:91], 1, s[44:45]
	v_or_b32_e32 v90, 16, v90
	s_waitcnt vmcnt(31)
	v_cvt_f32_ubyte1_e32 v93, v200
	v_cvt_f32_ubyte0_e32 v92, v200
	v_cvt_f32_ubyte3_e32 v95, v200
	v_cvt_f32_ubyte2_e32 v94, v200
	v_pk_mul_f32 v[92:93], v[2:3], v[92:93] op_sel_hi:[0,1]
	v_pk_mul_f32 v[94:95], v[2:3], v[94:95] op_sel_hi:[0,1]
	v_pk_mul_f32 v[80:81], v[80:81], v[92:93]
	v_pk_mul_f32 v[82:83], v[82:83], v[94:95]
	v_cvt_pk_bf16_f32 v80, v80, v81
	v_cvt_pk_bf16_f32 v81, v82, v83
	global_store_dwordx2 v[84:85], v[80:81], off
	v_lshl_add_u64 v[80:81], v[88:89], 0, s[26:27]
	v_lshl_add_u64 v[84:85], v[90:91], 1, s[44:45]
	s_waitcnt vmcnt(31)
	v_cvt_f32_ubyte1_e32 v87, v201
	v_cvt_f32_ubyte0_e32 v86, v201
	v_cvt_f32_ubyte3_e32 v89, v201
	v_cvt_f32_ubyte2_e32 v88, v201
	v_pk_mul_f32 v[86:87], v[2:3], v[86:87] op_sel_hi:[0,1]
	v_pk_mul_f32 v[88:89], v[2:3], v[88:89] op_sel_hi:[0,1]
	v_pk_mul_f32 v[76:77], v[76:77], v[86:87]
	v_pk_mul_f32 v[78:79], v[78:79], v[88:89]
	v_cvt_pk_bf16_f32 v76, v76, v77
	v_cvt_pk_bf16_f32 v77, v78, v79
	global_store_dwordx2 v[84:85], v[76:77], off
	v_lshl_add_u64 v[76:77], v[80:81], 1, s[44:45]
	v_or_b32_e32 v80, 16, v80
	s_waitcnt vmcnt(31)
	v_cvt_f32_ubyte1_e32 v83, v202
	v_cvt_f32_ubyte0_e32 v82, v202
	v_cvt_f32_ubyte3_e32 v85, v202
	v_cvt_f32_ubyte2_e32 v84, v202
	v_pk_mul_f32 v[82:83], v[2:3], v[82:83] op_sel_hi:[0,1]
	v_pk_mul_f32 v[84:85], v[2:3], v[84:85] op_sel_hi:[0,1]
	v_pk_mul_f32 v[72:73], v[72:73], v[82:83]
	v_pk_mul_f32 v[74:75], v[74:75], v[84:85]
	v_cvt_pk_bf16_f32 v72, v72, v73
	v_cvt_pk_bf16_f32 v73, v74, v75
	global_store_dwordx2 v[76:77], v[72:73], off
	v_lshl_add_u64 v[78:79], v[80:81], 1, s[44:45]
	v_lshl_add_u64 v[74:75], v[148:149], 0, s[28:29]
	v_lshl_add_u64 v[72:73], v[74:75], 0, s[26:27]
	v_or_b32_e32 v72, v72, v136
	v_or_b32_e32 v74, v74, v146
	s_waitcnt vmcnt(31)
	v_cvt_f32_ubyte1_e32 v81, v203
	v_cvt_f32_ubyte0_e32 v80, v203
	v_cvt_f32_ubyte3_e32 v83, v203
	v_cvt_f32_ubyte2_e32 v82, v203
	v_pk_mul_f32 v[80:81], v[2:3], v[80:81] op_sel_hi:[0,1]
	v_pk_mul_f32 v[2:3], v[2:3], v[82:83] op_sel_hi:[0,1]
	v_pk_mul_f32 v[68:69], v[68:69], v[80:81]
	v_pk_mul_f32 v[2:3], v[70:71], v[2:3]
	v_cvt_pk_bf16_f32 v68, v68, v69
	v_cvt_pk_bf16_f32 v69, v2, v3
	global_store_dwordx2 v[78:79], v[68:69], off
	v_add_u32_e32 v2, 12, v161
	ds_read2st64_b32 v[68:69], v2 offset0:8 offset1:9
	ds_read2st64_b32 v[2:3], v2 offset0:10 offset1:11
	v_lshl_add_u64 v[70:71], v[72:73], 1, s[44:45]
	v_or_b32_e32 v72, 16, v72
	s_waitcnt lgkmcnt(1)
	v_mul_f32_e32 v68, 0x3b808081, v68
	s_waitcnt lgkmcnt(0)
	v_mul_f32_e32 v2, 0x3b808081, v2
	s_waitcnt vmcnt(31)
	v_cvt_f32_ubyte1_e32 v79, v204
	v_cvt_f32_ubyte0_e32 v78, v204
	v_cvt_f32_ubyte3_e32 v81, v204
	v_cvt_f32_ubyte2_e32 v80, v204
	v_pk_mul_f32 v[78:79], v[68:69], v[78:79] op_sel_hi:[0,1]
	v_pk_mul_f32 v[80:81], v[68:69], v[80:81] op_sel_hi:[0,1]
	v_pk_mul_f32 v[64:65], v[64:65], v[78:79]
	v_pk_mul_f32 v[66:67], v[66:67], v[80:81]
	v_cvt_pk_bf16_f32 v64, v64, v65
	v_cvt_pk_bf16_f32 v65, v66, v67
	global_store_dwordx2 v[70:71], v[64:65], off
	v_lshl_add_u64 v[64:65], v[74:75], 0, s[26:27]
	v_lshl_add_u64 v[70:71], v[72:73], 1, s[44:45]
	s_waitcnt vmcnt(31)
	v_cvt_f32_ubyte1_e32 v73, v205
	v_cvt_f32_ubyte0_e32 v72, v205
	v_cvt_f32_ubyte3_e32 v75, v205
	v_cvt_f32_ubyte2_e32 v74, v205
	v_pk_mul_f32 v[72:73], v[68:69], v[72:73] op_sel_hi:[0,1]
	v_pk_mul_f32 v[74:75], v[68:69], v[74:75] op_sel_hi:[0,1]
	v_pk_mul_f32 v[60:61], v[60:61], v[72:73]
	v_pk_mul_f32 v[62:63], v[62:63], v[74:75]
	v_cvt_pk_bf16_f32 v60, v60, v61
	v_cvt_pk_bf16_f32 v61, v62, v63
	global_store_dwordx2 v[70:71], v[60:61], off
	v_lshl_add_u64 v[60:61], v[64:65], 1, s[44:45]
	v_or_b32_e32 v64, 16, v64
	s_waitcnt vmcnt(31)
; DI unsigned pk2(float a, float b) { f32x2 v = {a, b}; return __builtin_bit_cast(unsigned, __builtin_convertvector(v, bfv2)); }
; DI float bflo(unsigned u) { return __uint_as_float(u << 16); }
; DI float bfhi(unsigned u) { return __uint_as_float(u & 0xffff0000u); }
;     DI void operator()(const pg8::f32x4 (&acc)[2][2][4][2], const pg8::Unit& u, int wr, int wc, int fr, int fq) const {
;     ...
;                 const size_t tok = (size_t)u.pm * 256 + ai * 128 + wr * 64 + m * 16 + fr;
; #pragma unroll
;                 for (int bj = 0; bj < 2; ++bj)
; #pragma unroll
;                     for (int n = 0; n < 2; ++n) {
;                         const size_t off = tok * 1024 + u.pn * 256 + bj * 128 + wc * 32 + n * 16 + 4 * fq;
;                         const unsigned ug = *(const unsigned*)(sg + off);
;                         const float q = (PASS == 0 ? tab[(ai * 128 + wr * 64 + m * 16 + fr) * 4 + 3] : 1.0f) * (1.0f / 255.0f);
;                         float m0 = (float)(ug & 255u) * q * acc[ai][bj][m][n][0], m1 = (float)((ug >> 8) & 255u) * q * acc[ai][bj][m][n][1];
;                         float m2 = (float)((ug >> 16) & 255u) * q * acc[ai][bj][m][n][2], m3 = (float)(ug >> 24) * q * acc[ai][bj][m][n][3];
;                         if (PASS == 1) { const u32x2 t = *(const u32x2*)(merged + off); m0 += bflo(t.x); m1 += bfhi(t.x); m2 += bflo(t.y); m3 += bfhi(t.y); }
;                         u32x2 o; o.x = pk2(m0, m1); o.y = pk2(m2, m3);
;                         *(u32x2*)(merged + off) = o;
	v_cvt_f32_ubyte1_e32 v67, v206
	v_cvt_f32_ubyte0_e32 v66, v206
	v_cvt_f32_ubyte3_e32 v71, v206
	v_cvt_f32_ubyte2_e32 v70, v206
	v_pk_mul_f32 v[66:67], v[68:69], v[66:67] op_sel_hi:[0,1]
	v_pk_mul_f32 v[70:71], v[68:69], v[70:71] op_sel_hi:[0,1]
	v_pk_mul_f32 v[56:57], v[56:57], v[66:67]
	v_pk_mul_f32 v[58:59], v[58:59], v[70:71]
	v_cvt_pk_bf16_f32 v56, v56, v57
	v_cvt_pk_bf16_f32 v57, v58, v59
	global_store_dwordx2 v[60:61], v[56:57], off
	v_lshl_add_u64 v[62:63], v[64:65], 1, s[44:45]
	v_lshl_add_u64 v[56:57], v[150:151], 0, s[28:29]
	v_lshl_add_u64 v[58:59], v[56:57], 0, s[26:27]
	v_or_b32_e32 v58, v58, v136
	v_or_b32_e32 v56, v56, v146
	s_waitcnt vmcnt(31)
	v_cvt_f32_ubyte1_e32 v65, v207
	v_cvt_f32_ubyte0_e32 v64, v207
	v_cvt_f32_ubyte3_e32 v67, v207
	v_cvt_f32_ubyte2_e32 v66, v207
	v_pk_mul_f32 v[64:65], v[68:69], v[64:65] op_sel_hi:[0,1]
	v_pk_mul_f32 v[66:67], v[68:69], v[66:67] op_sel_hi:[0,1]
	v_pk_mul_f32 v[52:53], v[52:53], v[64:65]
	v_pk_mul_f32 v[54:55], v[54:55], v[66:67]
	v_cvt_pk_bf16_f32 v52, v52, v53
	v_cvt_pk_bf16_f32 v53, v54, v55
	global_store_dwordx2 v[62:63], v[52:53], off
	v_mul_f32_e32 v60, 0x3b808081, v69
	v_lshl_add_u64 v[52:53], v[58:59], 1, s[44:45]
	v_or_b32_e32 v58, 16, v58
	s_waitcnt vmcnt(31)
	v_cvt_f32_ubyte1_e32 v63, v208
	v_cvt_f32_ubyte0_e32 v62, v208
	v_cvt_f32_ubyte3_e32 v65, v208
	v_cvt_f32_ubyte2_e32 v64, v208
	v_pk_mul_f32 v[62:63], v[60:61], v[62:63] op_sel_hi:[0,1]
	v_pk_mul_f32 v[64:65], v[60:61], v[64:65] op_sel_hi:[0,1]
	v_pk_mul_f32 v[48:49], v[48:49], v[62:63]
	v_pk_mul_f32 v[50:51], v[50:51], v[64:65]
	v_cvt_pk_bf16_f32 v48, v48, v49
	v_cvt_pk_bf16_f32 v49, v50, v51
	global_store_dwordx2 v[52:53], v[48:49], off
	v_lshl_add_u64 v[48:49], v[56:57], 0, s[26:27]
	v_lshl_add_u64 v[52:53], v[58:59], 1, s[44:45]
	s_waitcnt vmcnt(31)
	v_cvt_f32_ubyte1_e32 v55, v209
	v_cvt_f32_ubyte0_e32 v54, v209
	v_cvt_f32_ubyte3_e32 v57, v209
	v_cvt_f32_ubyte2_e32 v56, v209
	v_pk_mul_f32 v[54:55], v[60:61], v[54:55] op_sel_hi:[0,1]
	v_pk_mul_f32 v[56:57], v[60:61], v[56:57] op_sel_hi:[0,1]
	v_pk_mul_f32 v[44:45], v[44:45], v[54:55]
	v_pk_mul_f32 v[46:47], v[46:47], v[56:57]
	v_cvt_pk_bf16_f32 v44, v44, v45
	v_cvt_pk_bf16_f32 v45, v46, v47
	global_store_dwordx2 v[52:53], v[44:45], off
	v_lshl_add_u64 v[44:45], v[48:49], 1, s[44:45]
	v_or_b32_e32 v48, 16, v48
	s_waitcnt vmcnt(31)
	v_cvt_f32_ubyte1_e32 v51, v210
	v_cvt_f32_ubyte0_e32 v50, v210
	v_cvt_f32_ubyte3_e32 v53, v210
	v_cvt_f32_ubyte2_e32 v52, v210
	v_pk_mul_f32 v[50:51], v[60:61], v[50:51] op_sel_hi:[0,1]
	v_pk_mul_f32 v[52:53], v[60:61], v[52:53] op_sel_hi:[0,1]
	v_pk_mul_f32 v[40:41], v[40:41], v[50:51]
	v_pk_mul_f32 v[42:43], v[42:43], v[52:53]
	v_cvt_pk_bf16_f32 v40, v40, v41
	v_cvt_pk_bf16_f32 v41, v42, v43
	global_store_dwordx2 v[44:45], v[40:41], off
	v_lshl_add_u64 v[46:47], v[48:49], 1, s[44:45]
	v_lshl_add_u64 v[40:41], v[152:153], 0, s[28:29]
	v_lshl_add_u64 v[42:43], v[40:41], 0, s[26:27]
	v_or_b32_e32 v42, v42, v136
	v_or_b32_e32 v40, v40, v146
	s_waitcnt vmcnt(31)
	v_cvt_f32_ubyte1_e32 v49, v211
	v_cvt_f32_ubyte0_e32 v48, v211
	v_cvt_f32_ubyte3_e32 v51, v211
	v_cvt_f32_ubyte2_e32 v50, v211
	v_pk_mul_f32 v[48:49], v[60:61], v[48:49] op_sel_hi:[0,1]
	v_pk_mul_f32 v[50:51], v[60:61], v[50:51] op_sel_hi:[0,1]
	v_pk_mul_f32 v[36:37], v[36:37], v[48:49]
	v_pk_mul_f32 v[38:39], v[38:39], v[50:51]
	v_cvt_pk_bf16_f32 v36, v36, v37
	v_cvt_pk_bf16_f32 v37, v38, v39
	global_store_dwordx2 v[46:47], v[36:37], off
	v_lshl_add_u64 v[36:37], v[42:43], 1, s[44:45]
	v_or_b32_e32 v42, 16, v42
	s_waitcnt vmcnt(31)
	v_cvt_f32_ubyte1_e32 v45, v212
	v_cvt_f32_ubyte0_e32 v44, v212
	v_cvt_f32_ubyte3_e32 v47, v212
	v_cvt_f32_ubyte2_e32 v46, v212
	v_pk_mul_f32 v[44:45], v[2:3], v[44:45] op_sel_hi:[0,1]
	v_pk_mul_f32 v[46:47], v[2:3], v[46:47] op_sel_hi:[0,1]
	v_pk_mul_f32 v[32:33], v[32:33], v[44:45]
	v_pk_mul_f32 v[34:35], v[34:35], v[46:47]
	v_cvt_pk_bf16_f32 v32, v32, v33
	v_cvt_pk_bf16_f32 v33, v34, v35
	global_store_dwordx2 v[36:37], v[32:33], off
	v_lshl_add_u64 v[32:33], v[40:41], 0, s[26:27]
	v_lshl_add_u64 v[36:37], v[42:43], 1, s[44:45]
	s_waitcnt vmcnt(31)
; DI unsigned pk2(float a, float b) { f32x2 v = {a, b}; return __builtin_bit_cast(unsigned, __builtin_convertvector(v, bfv2)); }
; DI float bflo(unsigned u) { return __uint_as_float(u << 16); }
; DI float bfhi(unsigned u) { return __uint_as_float(u & 0xffff0000u); }
;     DI void operator()(const pg8::f32x4 (&acc)[2][2][4][2], const pg8::Unit& u, int wr, int wc, int fr, int fq) const {
;     ...
;                 const size_t tok = (size_t)u.pm * 256 + ai * 128 + wr * 64 + m * 16 + fr;
; #pragma unroll
;                 for (int bj = 0; bj < 2; ++bj)
; #pragma unroll
;                     for (int n = 0; n < 2; ++n) {
;                         const size_t off = tok * 1024 + u.pn * 256 + bj * 128 + wc * 32 + n * 16 + 4 * fq;
;                         const unsigned ug = *(const unsigned*)(sg + off);
;                         const float q = (PASS == 0 ? tab[(ai * 128 + wr * 64 + m * 16 + fr) * 4 + 3] : 1.0f) * (1.0f / 255.0f);
;                         float m0 = (float)(ug & 255u) * q * acc[ai][bj][m][n][0], m1 = (float)((ug >> 8) & 255u) * q * acc[ai][bj][m][n][1];
;                         float m2 = (float)((ug >> 16) & 255u) * q * acc[ai][bj][m][n][2], m3 = (float)(ug >> 24) * q * acc[ai][bj][m][n][3];
;                         if (PASS == 1) { const u32x2 t = *(const u32x2*)(merged + off); m0 += bflo(t.x); m1 += bfhi(t.x); m2 += bflo(t.y); m3 += bfhi(t.y); }
;                         u32x2 o; o.x = pk2(m0, m1); o.y = pk2(m2, m3);
;                         *(u32x2*)(merged + off) = o;
	v_cvt_f32_ubyte1_e32 v39, v213
	v_cvt_f32_ubyte0_e32 v38, v213
	v_cvt_f32_ubyte3_e32 v41, v213
	v_cvt_f32_ubyte2_e32 v40, v213
	v_pk_mul_f32 v[38:39], v[2:3], v[38:39] op_sel_hi:[0,1]
	v_pk_mul_f32 v[40:41], v[2:3], v[40:41] op_sel_hi:[0,1]
	v_pk_mul_f32 v[28:29], v[28:29], v[38:39]
	v_pk_mul_f32 v[30:31], v[30:31], v[40:41]
	v_cvt_pk_bf16_f32 v28, v28, v29
	v_cvt_pk_bf16_f32 v29, v30, v31
	global_store_dwordx2 v[36:37], v[28:29], off
	v_lshl_add_u64 v[28:29], v[32:33], 1, s[44:45]
	v_or_b32_e32 v32, 16, v32
	s_waitcnt vmcnt(31)
	v_cvt_f32_ubyte1_e32 v35, v214
	v_cvt_f32_ubyte0_e32 v34, v214
	v_cvt_f32_ubyte3_e32 v37, v214
	v_cvt_f32_ubyte2_e32 v36, v214
	v_pk_mul_f32 v[34:35], v[2:3], v[34:35] op_sel_hi:[0,1]
	v_pk_mul_f32 v[36:37], v[2:3], v[36:37] op_sel_hi:[0,1]
	v_pk_mul_f32 v[24:25], v[24:25], v[34:35]
	v_pk_mul_f32 v[26:27], v[26:27], v[36:37]
	v_cvt_pk_bf16_f32 v24, v24, v25
	v_cvt_pk_bf16_f32 v25, v26, v27
	global_store_dwordx2 v[28:29], v[24:25], off
	v_lshl_add_u64 v[30:31], v[32:33], 1, s[44:45]
	v_lshl_add_u64 v[24:25], v[154:155], 0, s[28:29]
	v_lshl_add_u64 v[26:27], v[24:25], 0, s[26:27]
	v_or_b32_e32 v26, v26, v136
	v_or_b32_e32 v24, v24, v146
	s_waitcnt vmcnt(31)
	v_cvt_f32_ubyte1_e32 v33, v215
	v_cvt_f32_ubyte0_e32 v32, v215
	v_cvt_f32_ubyte3_e32 v35, v215
	v_cvt_f32_ubyte2_e32 v34, v215
	v_pk_mul_f32 v[32:33], v[2:3], v[32:33] op_sel_hi:[0,1]
	v_pk_mul_f32 v[34:35], v[2:3], v[34:35] op_sel_hi:[0,1]
	v_pk_mul_f32 v[20:21], v[20:21], v[32:33]
	v_pk_mul_f32 v[22:23], v[22:23], v[34:35]
	v_cvt_pk_bf16_f32 v20, v20, v21
	v_cvt_pk_bf16_f32 v21, v22, v23
	global_store_dwordx2 v[30:31], v[20:21], off
	v_mul_f32_e32 v2, 0x3b808081, v3
	v_lshl_add_u64 v[20:21], v[26:27], 1, s[44:45]
	v_or_b32_e32 v26, 16, v26
	s_waitcnt vmcnt(31)
	v_cvt_f32_ubyte1_e32 v29, v216
	v_cvt_f32_ubyte0_e32 v28, v216
	v_cvt_f32_ubyte3_e32 v31, v216
	v_cvt_f32_ubyte2_e32 v30, v216
	v_pk_mul_f32 v[28:29], v[2:3], v[28:29] op_sel_hi:[0,1]
	v_pk_mul_f32 v[30:31], v[2:3], v[30:31] op_sel_hi:[0,1]
	v_pk_mul_f32 v[16:17], v[16:17], v[28:29]
	v_pk_mul_f32 v[18:19], v[18:19], v[30:31]
	v_cvt_pk_bf16_f32 v16, v16, v17
	v_cvt_pk_bf16_f32 v17, v18, v19
	global_store_dwordx2 v[20:21], v[16:17], off
	v_lshl_add_u64 v[16:17], v[24:25], 0, s[26:27]
	v_lshl_add_u64 v[20:21], v[26:27], 1, s[44:45]
	s_waitcnt vmcnt(31)
	v_cvt_f32_ubyte1_e32 v23, v217
	v_cvt_f32_ubyte0_e32 v22, v217
	v_cvt_f32_ubyte3_e32 v25, v217
	v_cvt_f32_ubyte2_e32 v24, v217
	v_pk_mul_f32 v[22:23], v[2:3], v[22:23] op_sel_hi:[0,1]
	v_pk_mul_f32 v[24:25], v[2:3], v[24:25] op_sel_hi:[0,1]
	v_pk_mul_f32 v[12:13], v[12:13], v[22:23]
	v_pk_mul_f32 v[14:15], v[14:15], v[24:25]
	v_cvt_pk_bf16_f32 v12, v12, v13
	v_cvt_pk_bf16_f32 v13, v14, v15
	global_store_dwordx2 v[20:21], v[12:13], off
	v_lshl_add_u64 v[12:13], v[16:17], 1, s[44:45]
	v_or_b32_e32 v16, 16, v16
	s_waitcnt vmcnt(31)
	v_cvt_f32_ubyte1_e32 v19, v218
	v_cvt_f32_ubyte0_e32 v18, v218
	v_cvt_f32_ubyte3_e32 v21, v218
	v_cvt_f32_ubyte2_e32 v20, v218
	v_pk_mul_f32 v[18:19], v[2:3], v[18:19] op_sel_hi:[0,1]
	v_pk_mul_f32 v[20:21], v[2:3], v[20:21] op_sel_hi:[0,1]
	v_pk_mul_f32 v[8:9], v[8:9], v[18:19]
	v_pk_mul_f32 v[10:11], v[10:11], v[20:21]
	v_cvt_pk_bf16_f32 v8, v8, v9
	v_cvt_pk_bf16_f32 v9, v10, v11
	global_store_dwordx2 v[12:13], v[8:9], off
	v_lshl_add_u64 v[8:9], v[16:17], 1, s[44:45]
	s_waitcnt vmcnt(31)
	v_cvt_f32_ubyte1_e32 v11, v219
	v_cvt_f32_ubyte0_e32 v10, v219
	v_cvt_f32_ubyte3_e32 v13, v219
	v_cvt_f32_ubyte2_e32 v12, v219
	v_pk_mul_f32 v[10:11], v[2:3], v[10:11] op_sel_hi:[0,1]
	v_pk_mul_f32 v[2:3], v[2:3], v[12:13] op_sel_hi:[0,1]
	v_pk_mul_f32 v[4:5], v[4:5], v[10:11]
	v_pk_mul_f32 v[2:3], v[6:7], v[2:3]
	v_cvt_pk_bf16_f32 v4, v4, v5
	v_cvt_pk_bf16_f32 v5, v2, v3
	global_store_dwordx2 v[8:9], v[4:5], off
	s_cbranch_vccnz .LBB0_1914
	s_andn2_b64 vcc, exec, s[16:17]
	s_cbranch_vccnz .LBB0_1913
	s_barrier
	s_branch .LBB0_1913
